# GEMM3: last unit's epilogue stores written through (copy of the epilogue), lighter L2 write-back at barrier 6
# baseline (speedup 1.0000x reference)
; #define PG8_STAGE(bufoff, gbase, voff) do { _Pragma("unroll") for (int _i = 0; _i < 2; ++_i) \
;         __builtin_amdgcn_global_load_lds((const unsigned*)((const char*)(gbase) + (voff)[_i]), (LAS unsigned*)(lds + (bufoff) + ldsw + _i * 8192), 16, 0, 0); } while (0)
; #define PG8_LDA(dst, b, h) do { _Pragma("unroll") for (int m = 0; m < 4; ++m) _Pragma("unroll") for (int k = 0; k < 2; ++k) dst[m][k] = *(const LAS bf16x8*)(lds + PG8_SA(b, h) + aoff + m * 2048 + k * 1024); } while (0)
; #define PG8_LDB(dst, b, h) do { _Pragma("unroll") for (int n = 0; n < 2; ++n) _Pragma("unroll") for (int k = 0; k < 2; ++k) dst[n][k] = *(const LAS bf16x8*)(lds + PG8_SB(b, h) + boff + n * 2048 + k * 1024); } while (0)
; #define PG8_MMA(ai, bj, At, Bt) do { __builtin_amdgcn_s_setprio(1); _Pragma("unroll") for (int m = 0; m < 4; ++m) _Pragma("unroll") for (int n = 0; n < 2; ++n) _Pragma("unroll") for (int k = 0; k < 2; ++k) \
;         acc[ai][bj][m][n] = __builtin_amdgcn_mfma_f32_16x16x32_bf16(Bt[n][k], At[m][k], acc[ai][bj][m][n], 0, 0, 0); __builtin_amdgcn_s_setprio(0); } while (0)
; #define PG8_WAIT_V(n) asm volatile("s_waitcnt vmcnt(" #n ")" ::: "memory")
; #define PG8_WAIT_L(n) asm volatile("s_waitcnt lgkmcnt(" #n ")" ::: "memory")
; #define PG8_BAR __builtin_amdgcn_s_barrier()
; #define PG8_SCHED __builtin_amdgcn_sched_barrier(0)
; template <class Epi>
; __device__ __forceinline__ void gemm_phase(LAS unsigned char* lds, const Gemm g, const StaticOrder& S, const Epi& E, float* smem = nullptr) {
;     ...
;             PG8_LDB(B0, 0, 0); PG8_SCHED; PG8_LDA(At, 0, 0); PG8_STAGE(PG8_SA(1, 1), a1 + hstep, voffA);
;             PG8_WAIT_L(8); PG8_BAR; PG8_WAIT_L(0); PG8_MMA(0, 0, At, B0); PG8_BAR; PG8_SCHED;
;             PG8_LDB(B1, 0, 1); PG8_STAGE(PG8_SB(0, 0), b2, voffA);
;             PG8_BAR; PG8_WAIT_L(0); PG8_MMA(0, 1, At, B1); PG8_BAR;
;             PG8_LDA(At, 0, 1); PG8_STAGE(PG8_SA(0, 0), a2, voffA);
;             PG8_BAR; PG8_WAIT_L(0); PG8_MMA(1, 0, At, B0); PG8_BAR; PG8_SCHED;
;             PG8_STAGE(PG8_SB(0, 1), b2 + hstep, voffA);
;             PG8_WAIT_V(6); PG8_BAR; PG8_MMA(1, 1, At, B1); PG8_BAR;
.LBB0_668:
	ds_read_b128 v[150:153], v146
	ds_read_b128 v[154:157], v146 offset:1024
	ds_read_b128 v[158:161], v146 offset:2048
	ds_read_b128 v[162:165], v146 offset:3072
	s_add_u32 s64, s62, 0xfffc0080
	s_addc_u32 s65, s63, -1
	s_cmp_eq_u32 s85, 12
	s_cselect_b32 s67, s47, s65
	s_cselect_b32 s66, s81, s64
	s_cselect_b32 s65, s45, s84
	s_cselect_b32 s64, s82, s83
	v_lshl_add_u64 v[142:143], s[62:63], 0, v[134:135]
	s_add_i32 m0, s60, 0xc000
	ds_read_b128 v[166:169], v147
	ds_read_b128 v[170:173], v147 offset:1024
	ds_read_b128 v[174:177], v147 offset:2048
	ds_read_b128 v[178:181], v147 offset:3072
	ds_read_b128 v[182:185], v147 offset:4096
	ds_read_b128 v[186:189], v147 offset:5120
	ds_read_b128 v[190:193], v147 offset:6144
	ds_read_b128 v[194:197], v147 offset:7168
	global_load_lds_dwordx4 v[142:143], off
	v_lshl_add_u64 v[142:143], s[62:63], 0, v[136:137]
	s_add_i32 m0, s60, 0xe000
	s_nop 0
	global_load_lds_dwordx4 v[142:143], off
	s_waitcnt lgkmcnt(8)
	s_barrier
	s_waitcnt lgkmcnt(0)
	s_waitcnt lgkmcnt(0)
	v_mfma_f32_16x16x32_bf16 v[124:127], v[150:153], v[166:169], v[124:127]
	v_mfma_f32_16x16x32_bf16 v[120:123], v[158:161], v[166:169], v[120:123]
	v_mfma_f32_16x16x32_bf16 v[108:111], v[150:153], v[174:177], v[108:111]
	v_mfma_f32_16x16x32_bf16 v[104:107], v[158:161], v[174:177], v[104:107]
	v_mfma_f32_16x16x32_bf16 v[92:95], v[150:153], v[182:185], v[92:95]
	v_mfma_f32_16x16x32_bf16 v[88:91], v[158:161], v[182:185], v[88:91]
	v_mfma_f32_16x16x32_bf16 v[76:79], v[150:153], v[190:193], v[76:79]
	v_mfma_f32_16x16x32_bf16 v[72:75], v[158:161], v[190:193], v[72:75]
	v_mfma_f32_16x16x32_bf16 v[124:127], v[154:157], v[170:173], v[124:127]
	v_mfma_f32_16x16x32_bf16 v[120:123], v[162:165], v[170:173], v[120:123]
	v_mfma_f32_16x16x32_bf16 v[108:111], v[154:157], v[178:181], v[108:111]
	v_mfma_f32_16x16x32_bf16 v[104:107], v[162:165], v[178:181], v[104:107]
	v_mfma_f32_16x16x32_bf16 v[92:95], v[154:157], v[186:189], v[92:95]
	v_mfma_f32_16x16x32_bf16 v[88:91], v[162:165], v[186:189], v[88:91]
	v_mfma_f32_16x16x32_bf16 v[76:79], v[154:157], v[194:197], v[76:79]
	v_mfma_f32_16x16x32_bf16 v[72:75], v[162:165], v[194:197], v[72:75]
	s_barrier
	s_add_i32 s86, s74, s33
	v_lshl_add_u64 v[142:143], s[64:65], 0, v[128:129]
	s_mov_b32 m0, s86
	ds_read_b128 v[198:201], v148
	ds_read_b128 v[202:205], v148 offset:1024
	ds_read_b128 v[206:209], v148 offset:2048
	ds_read_b128 v[210:213], v148 offset:3072
	global_load_lds_dwordx4 v[142:143], off
	v_lshl_add_u64 v[214:215], s[64:65], 0, v[130:131]
	s_add_i32 m0, s86, 0x2000
	s_nop 0
	global_load_lds_dwordx4 v[214:215], off
	s_barrier
	s_waitcnt lgkmcnt(0)
	s_waitcnt lgkmcnt(0)
	v_mfma_f32_16x16x32_bf16 v[116:119], v[198:201], v[166:169], v[116:119]
	v_mfma_f32_16x16x32_bf16 v[112:115], v[206:209], v[166:169], v[112:115]
	v_mfma_f32_16x16x32_bf16 v[100:103], v[198:201], v[174:177], v[100:103]
	v_mfma_f32_16x16x32_bf16 v[96:99], v[206:209], v[174:177], v[96:99]
	v_mfma_f32_16x16x32_bf16 v[84:87], v[198:201], v[182:185], v[84:87]
	v_mfma_f32_16x16x32_bf16 v[80:83], v[206:209], v[182:185], v[80:83]
	v_mfma_f32_16x16x32_bf16 v[68:71], v[198:201], v[190:193], v[68:71]
	v_mfma_f32_16x16x32_bf16 v[64:67], v[206:209], v[190:193], v[64:67]
	v_mfma_f32_16x16x32_bf16 v[116:119], v[202:205], v[170:173], v[116:119]
	v_mfma_f32_16x16x32_bf16 v[112:115], v[210:213], v[170:173], v[112:115]
	v_mfma_f32_16x16x32_bf16 v[100:103], v[202:205], v[178:181], v[100:103]
	v_mfma_f32_16x16x32_bf16 v[96:99], v[210:213], v[178:181], v[96:99]
	v_mfma_f32_16x16x32_bf16 v[84:87], v[202:205], v[186:189], v[84:87]
	v_mfma_f32_16x16x32_bf16 v[80:83], v[210:213], v[186:189], v[80:83]
	v_mfma_f32_16x16x32_bf16 v[68:71], v[202:205], v[194:197], v[68:71]
	v_mfma_f32_16x16x32_bf16 v[64:67], v[210:213], v[194:197], v[64:67]
	s_mov_b32 m0, s60
	v_lshl_add_u64 v[216:217], s[66:67], 0, v[128:129]
	s_barrier
	ds_read_b128 v[166:169], v147 offset:16384
	ds_read_b128 v[170:173], v147 offset:17408
	ds_read_b128 v[174:177], v147 offset:18432
	ds_read_b128 v[178:181], v147 offset:19456
	ds_read_b128 v[182:185], v147 offset:20480
	ds_read_b128 v[186:189], v147 offset:21504
	ds_read_b128 v[190:193], v147 offset:22528
	ds_read_b128 v[194:197], v147 offset:23552
	global_load_lds_dwordx4 v[216:217], off
	v_lshl_add_u64 v[218:219], s[66:67], 0, v[130:131]
	s_mov_b32 m0, s61
	s_nop 0
	global_load_lds_dwordx4 v[218:219], off
	s_barrier
	s_waitcnt lgkmcnt(0)
	s_waitcnt lgkmcnt(0)
	v_mfma_f32_16x16x32_bf16 v[60:63], v[150:153], v[166:169], v[60:63]
	v_mfma_f32_16x16x32_bf16 v[56:59], v[158:161], v[166:169], v[56:59]
	v_mfma_f32_16x16x32_bf16 v[44:47], v[150:153], v[174:177], v[44:47]
	v_mfma_f32_16x16x32_bf16 v[40:43], v[158:161], v[174:177], v[40:43]
	v_mfma_f32_16x16x32_bf16 v[28:31], v[150:153], v[182:185], v[28:31]
	v_mfma_f32_16x16x32_bf16 v[24:27], v[158:161], v[182:185], v[24:27]
	v_mfma_f32_16x16x32_bf16 v[12:15], v[150:153], v[190:193], v[12:15]
	v_mfma_f32_16x16x32_bf16 v[8:11], v[158:161], v[190:193], v[8:11]
	v_mfma_f32_16x16x32_bf16 v[60:63], v[154:157], v[170:173], v[60:63]
	v_mfma_f32_16x16x32_bf16 v[56:59], v[162:165], v[170:173], v[56:59]
	v_mfma_f32_16x16x32_bf16 v[44:47], v[154:157], v[178:181], v[44:47]
	v_mfma_f32_16x16x32_bf16 v[40:43], v[162:165], v[178:181], v[40:43]
	v_mfma_f32_16x16x32_bf16 v[28:31], v[154:157], v[186:189], v[28:31]
	v_mfma_f32_16x16x32_bf16 v[24:27], v[162:165], v[186:189], v[24:27]
	v_mfma_f32_16x16x32_bf16 v[12:15], v[154:157], v[194:197], v[12:15]
	v_mfma_f32_16x16x32_bf16 v[8:11], v[162:165], v[194:197], v[8:11]
	s_barrier
; #define PG8_STAGE(bufoff, gbase, voff) do { _Pragma("unroll") for (int _i = 0; _i < 2; ++_i) \
;         __builtin_amdgcn_global_load_lds((const unsigned*)((const char*)(gbase) + (voff)[_i]), (LAS unsigned*)(lds + (bufoff) + ldsw + _i * 8192), 16, 0, 0); } while (0)
; #define PG8_LDA(dst, b, h) do { _Pragma("unroll") for (int m = 0; m < 4; ++m) _Pragma("unroll") for (int k = 0; k < 2; ++k) dst[m][k] = *(const LAS bf16x8*)(lds + PG8_SA(b, h) + aoff + m * 2048 + k * 1024); } while (0)
; #define PG8_LDB(dst, b, h) do { _Pragma("unroll") for (int n = 0; n < 2; ++n) _Pragma("unroll") for (int k = 0; k < 2; ++k) dst[n][k] = *(const LAS bf16x8*)(lds + PG8_SB(b, h) + boff + n * 2048 + k * 1024); } while (0)
; #define PG8_MMA(ai, bj, At, Bt) do { __builtin_amdgcn_s_setprio(1); _Pragma("unroll") for (int m = 0; m < 4; ++m) _Pragma("unroll") for (int n = 0; n < 2; ++n) _Pragma("unroll") for (int k = 0; k < 2; ++k) \
;         acc[ai][bj][m][n] = __builtin_amdgcn_mfma_f32_16x16x32_bf16(Bt[n][k], At[m][k], acc[ai][bj][m][n], 0, 0, 0); __builtin_amdgcn_s_setprio(0); } while (0)
; #define PG8_WAIT_V(n) asm volatile("s_waitcnt vmcnt(" #n ")" ::: "memory")
; #define PG8_WAIT_L(n) asm volatile("s_waitcnt lgkmcnt(" #n ")" ::: "memory")
; #define PG8_BAR __builtin_amdgcn_s_barrier()
; #define PG8_SCHED __builtin_amdgcn_sched_barrier(0)
; template <class Epi>
; __device__ __forceinline__ void gemm_phase(LAS unsigned char* lds, const Gemm g, const StaticOrder& S, const Epi& E, float* smem = nullptr) {
;     ...
;             PG8_STAGE(PG8_SB(0, 1), b2 + hstep, voffA);
;             PG8_WAIT_V(6); PG8_BAR; PG8_MMA(1, 1, At, B1); PG8_BAR;
;             PG8_LDB(B0, 1, 0); PG8_SCHED; PG8_LDA(At, 1, 0); PG8_STAGE(PG8_SA(0, 1), a2 + hstep, voffA);
;             PG8_WAIT_L(8); PG8_BAR; PG8_WAIT_L(0); PG8_MMA(0, 0, At, B0); PG8_BAR; PG8_SCHED;
;             PG8_LDB(B1, 1, 1); PG8_STAGE(PG8_SB(1, 0), b3, voffA);
;             PG8_BAR; PG8_WAIT_L(0); PG8_MMA(0, 1, At, B1); PG8_BAR;
;             PG8_LDA(At, 1, 1); PG8_STAGE(PG8_SA(1, 0), a3, voffA);
;             PG8_BAR; PG8_WAIT_L(0); PG8_MMA(1, 0, At, B0); PG8_BAR; PG8_SCHED;
;             PG8_STAGE(PG8_SB(1, 1), b3 + hstep, voffA);
;             PG8_WAIT_V(6); PG8_BAR; PG8_MMA(1, 1, At, B1); PG8_BAR;
	s_add_u32 s86, s64, 0x40000
	s_addc_u32 s87, s65, 0
	s_add_i32 s88, s75, s33
	v_lshl_add_u64 v[150:151], s[86:87], 0, v[128:129]
	s_mov_b32 m0, s88
	s_nop 0
	global_load_lds_dwordx4 v[150:151], off
	v_lshl_add_u64 v[150:151], s[86:87], 0, v[130:131]
	s_add_i32 m0, s88, 0x2000
	s_nop 0
	global_load_lds_dwordx4 v[150:151], off
	s_waitcnt vmcnt(6)
	s_barrier
	v_mfma_f32_16x16x32_bf16 v[52:55], v[198:201], v[166:169], v[52:55]
	v_mfma_f32_16x16x32_bf16 v[48:51], v[206:209], v[166:169], v[48:51]
	v_mfma_f32_16x16x32_bf16 v[36:39], v[198:201], v[174:177], v[36:39]
	v_mfma_f32_16x16x32_bf16 v[32:35], v[206:209], v[174:177], v[32:35]
	v_mfma_f32_16x16x32_bf16 v[20:23], v[198:201], v[182:185], v[20:23]
	v_mfma_f32_16x16x32_bf16 v[16:19], v[206:209], v[182:185], v[16:19]
	v_mfma_f32_16x16x32_bf16 v[4:7], v[198:201], v[190:193], v[4:7]
	v_mfma_f32_16x16x32_bf16 v[0:3], v[206:209], v[190:193], v[0:3]
	v_mfma_f32_16x16x32_bf16 v[52:55], v[202:205], v[170:173], v[52:55]
	v_mfma_f32_16x16x32_bf16 v[48:51], v[210:213], v[170:173], v[48:51]
	v_mfma_f32_16x16x32_bf16 v[36:39], v[202:205], v[178:181], v[36:39]
	v_mfma_f32_16x16x32_bf16 v[32:35], v[210:213], v[178:181], v[32:35]
	v_mfma_f32_16x16x32_bf16 v[20:23], v[202:205], v[186:189], v[20:23]
	v_mfma_f32_16x16x32_bf16 v[16:19], v[210:213], v[186:189], v[16:19]
	v_mfma_f32_16x16x32_bf16 v[4:7], v[202:205], v[194:197], v[4:7]
	v_mfma_f32_16x16x32_bf16 v[0:3], v[210:213], v[194:197], v[0:3]
	s_add_i32 s86, 16, 0x18000
	v_add_u32_e32 v149, s86, v145
	s_barrier
	ds_read_b128 v[150:153], v149
	ds_read_b128 v[154:157], v149 offset:1024
	ds_read_b128 v[158:161], v149 offset:2048
	ds_read_b128 v[162:165], v149 offset:3072
	s_add_u32 s66, s66, 0x40000
	s_addc_u32 s67, s67, 0
	s_mov_b32 m0, s68
	v_lshl_add_u64 v[198:199], s[66:67], 0, v[128:129]
	ds_read_b128 v[166:169], v147 offset:32768
	ds_read_b128 v[170:173], v147 offset:33792
	ds_read_b128 v[174:177], v147 offset:34816
	ds_read_b128 v[178:181], v147 offset:35840
	ds_read_b128 v[182:185], v147 offset:36864
	ds_read_b128 v[186:189], v147 offset:37888
	ds_read_b128 v[190:193], v147 offset:38912
	ds_read_b128 v[194:197], v147 offset:39936
	global_load_lds_dwordx4 v[198:199], off
	v_lshl_add_u64 v[198:199], s[66:67], 0, v[130:131]
	s_mov_b32 m0, s69
	s_nop 0
	global_load_lds_dwordx4 v[198:199], off
	s_waitcnt lgkmcnt(8)
	s_barrier
	s_waitcnt lgkmcnt(0)
	s_waitcnt lgkmcnt(0)
	v_mfma_f32_16x16x32_bf16 v[124:127], v[150:153], v[166:169], v[124:127]
	v_mfma_f32_16x16x32_bf16 v[120:123], v[158:161], v[166:169], v[120:123]
	v_mfma_f32_16x16x32_bf16 v[108:111], v[150:153], v[174:177], v[108:111]
	v_mfma_f32_16x16x32_bf16 v[104:107], v[158:161], v[174:177], v[104:107]
	v_mfma_f32_16x16x32_bf16 v[92:95], v[150:153], v[182:185], v[92:95]
	v_mfma_f32_16x16x32_bf16 v[88:91], v[158:161], v[182:185], v[88:91]
	v_mfma_f32_16x16x32_bf16 v[76:79], v[150:153], v[190:193], v[76:79]
	v_mfma_f32_16x16x32_bf16 v[72:75], v[158:161], v[190:193], v[72:75]
	v_mfma_f32_16x16x32_bf16 v[124:127], v[154:157], v[170:173], v[124:127]
	v_mfma_f32_16x16x32_bf16 v[120:123], v[162:165], v[170:173], v[120:123]
	v_mfma_f32_16x16x32_bf16 v[108:111], v[154:157], v[178:181], v[108:111]
	v_mfma_f32_16x16x32_bf16 v[104:107], v[162:165], v[178:181], v[104:107]
	v_mfma_f32_16x16x32_bf16 v[92:95], v[154:157], v[186:189], v[92:95]
	v_mfma_f32_16x16x32_bf16 v[88:91], v[162:165], v[186:189], v[88:91]
	v_mfma_f32_16x16x32_bf16 v[76:79], v[154:157], v[194:197], v[76:79]
	v_mfma_f32_16x16x32_bf16 v[72:75], v[162:165], v[194:197], v[72:75]
	s_barrier
	s_add_i32 s66, 16, 0x1c000
	s_add_i32 s67, s86, s33
	v_add_u32_e32 v149, s66, v145
	v_lshl_add_u64 v[142:143], v[142:143], 0, s[0:1]
	s_mov_b32 m0, s67
	ds_read_b128 v[198:201], v149
	ds_read_b128 v[202:205], v149 offset:1024
	ds_read_b128 v[206:209], v149 offset:2048
	ds_read_b128 v[210:213], v149 offset:3072
	global_load_lds_dwordx4 v[142:143], off
	v_lshl_add_u64 v[142:143], v[214:215], 0, s[0:1]
	s_add_i32 m0, s67, 0x2000
	s_nop 0
	global_load_lds_dwordx4 v[142:143], off
	s_barrier
	s_waitcnt lgkmcnt(0)
	s_waitcnt lgkmcnt(0)
	v_mfma_f32_16x16x32_bf16 v[116:119], v[198:201], v[166:169], v[116:119]
	v_mfma_f32_16x16x32_bf16 v[112:115], v[206:209], v[166:169], v[112:115]
	v_mfma_f32_16x16x32_bf16 v[100:103], v[198:201], v[174:177], v[100:103]
	v_mfma_f32_16x16x32_bf16 v[96:99], v[206:209], v[174:177], v[96:99]
	v_mfma_f32_16x16x32_bf16 v[84:87], v[198:201], v[182:185], v[84:87]
	v_mfma_f32_16x16x32_bf16 v[80:83], v[206:209], v[182:185], v[80:83]
	v_mfma_f32_16x16x32_bf16 v[68:71], v[198:201], v[190:193], v[68:71]
	v_mfma_f32_16x16x32_bf16 v[64:67], v[206:209], v[190:193], v[64:67]
	v_mfma_f32_16x16x32_bf16 v[116:119], v[202:205], v[170:173], v[116:119]
	v_mfma_f32_16x16x32_bf16 v[112:115], v[210:213], v[170:173], v[112:115]
	v_mfma_f32_16x16x32_bf16 v[100:103], v[202:205], v[178:181], v[100:103]
	v_mfma_f32_16x16x32_bf16 v[96:99], v[210:213], v[178:181], v[96:99]
	v_mfma_f32_16x16x32_bf16 v[84:87], v[202:205], v[186:189], v[84:87]
	v_mfma_f32_16x16x32_bf16 v[80:83], v[210:213], v[186:189], v[80:83]
	v_mfma_f32_16x16x32_bf16 v[68:71], v[202:205], v[194:197], v[68:71]
	v_mfma_f32_16x16x32_bf16 v[64:67], v[210:213], v[194:197], v[64:67]
	s_mov_b32 m0, s70
	v_lshl_add_u64 v[142:143], v[216:217], 0, s[0:1]
	s_barrier
	ds_read_b128 v[166:169], v147 offset:49152
	ds_read_b128 v[170:173], v147 offset:50176
	ds_read_b128 v[174:177], v147 offset:51200
	ds_read_b128 v[178:181], v147 offset:52224
	ds_read_b128 v[182:185], v147 offset:53248
	ds_read_b128 v[186:189], v147 offset:54272
	ds_read_b128 v[190:193], v147 offset:55296
	ds_read_b128 v[194:197], v147 offset:56320
	global_load_lds_dwordx4 v[142:143], off
	v_lshl_add_u64 v[142:143], v[218:219], 0, s[0:1]
	s_mov_b32 m0, s71
	s_nop 0
	global_load_lds_dwordx4 v[142:143], off
	s_barrier
; __device__ __forceinline__ void st_bf16x8(bf16_t* p, const f32x4 a, const f32x4 b) { uint4 o; o.x = cvt_pk_bf16(a[0], a[1]); o.y = cvt_pk_bf16(a[2], a[3]); o.z = cvt_pk_bf16(b[0], b[1]); o.w = cvt_pk_bf16(b[2], b[3]); *(uint4*)p = o; }
; #define PG8_STAGE(bufoff, gbase, voff) do { _Pragma("unroll") for (int _i = 0; _i < 2; ++_i) \
;         __builtin_amdgcn_global_load_lds((const unsigned*)((const char*)(gbase) + (voff)[_i]), (LAS unsigned*)(lds + (bufoff) + ldsw + _i * 8192), 16, 0, 0); } while (0)
; #define PG8_MMA(ai, bj, At, Bt) do { __builtin_amdgcn_s_setprio(1); _Pragma("unroll") for (int m = 0; m < 4; ++m) _Pragma("unroll") for (int n = 0; n < 2; ++n) _Pragma("unroll") for (int k = 0; k < 2; ++k) \
;         acc[ai][bj][m][n] = __builtin_amdgcn_mfma_f32_16x16x32_bf16(Bt[n][k], At[m][k], acc[ai][bj][m][n], 0, 0, 0); __builtin_amdgcn_s_setprio(0); } while (0)
; #define PG8_WAIT_V(n) asm volatile("s_waitcnt vmcnt(" #n ")" ::: "memory")
; #define PG8_WAIT_L(n) asm volatile("s_waitcnt lgkmcnt(" #n ")" ::: "memory")
; #define PG8_BAR __builtin_amdgcn_s_barrier()
; #define PG8_SCHED __builtin_amdgcn_sched_barrier(0)
;     __device__ __forceinline__ void row(const f32x4 (&a)[2][2], int row, int pn, int wc, int fq) const {
;         bf16_t* rp = T + (size_t)row * DFF + pn * BM + wc * 32 + 8 * fq;
; #pragma unroll
;         for (int bj = 0; bj < 2; ++bj) { f32x4 v0 = a[bj][0], v1 = a[bj][1];
; #pragma unroll
;             for (int j = 0; j < 4; ++j) { const float r0 = fmaxf(v0[j], 0.f), r1 = fmaxf(v1[j], 0.f); v0[j] = r0 * r0; v1[j] = r1 * r1; }
;             st_bf16x8(rp + bj * HALF, v0, v1); }
; template <class Epi>
; __device__ __forceinline__ void gemm_phase(LAS unsigned char* lds, const Gemm g, const StaticOrder& S, const Epi& E, float* smem = nullptr) {
;     ...
;             PG8_BAR; PG8_WAIT_L(0); PG8_MMA(1, 0, At, B0); PG8_BAR; PG8_SCHED;
;             PG8_STAGE(PG8_SB(1, 1), b3 + hstep, voffA);
;             PG8_WAIT_V(6); PG8_BAR; PG8_MMA(1, 1, At, B1); PG8_BAR;
;         }
;         if constexpr (!Epi::AFTER_DRAIN) E(acc, cur, wr, wc, fr, fq);
	s_waitcnt lgkmcnt(0)
	s_waitcnt lgkmcnt(0)
	v_mfma_f32_16x16x32_bf16 v[60:63], v[150:153], v[166:169], v[60:63]
	v_mfma_f32_16x16x32_bf16 v[56:59], v[158:161], v[166:169], v[56:59]
	v_mfma_f32_16x16x32_bf16 v[44:47], v[150:153], v[174:177], v[44:47]
	v_mfma_f32_16x16x32_bf16 v[40:43], v[158:161], v[174:177], v[40:43]
	v_mfma_f32_16x16x32_bf16 v[28:31], v[150:153], v[182:185], v[28:31]
	v_mfma_f32_16x16x32_bf16 v[24:27], v[158:161], v[182:185], v[24:27]
	v_mfma_f32_16x16x32_bf16 v[12:15], v[150:153], v[190:193], v[12:15]
	v_mfma_f32_16x16x32_bf16 v[8:11], v[158:161], v[190:193], v[8:11]
	v_mfma_f32_16x16x32_bf16 v[60:63], v[154:157], v[170:173], v[60:63]
	v_mfma_f32_16x16x32_bf16 v[56:59], v[162:165], v[170:173], v[56:59]
	v_mfma_f32_16x16x32_bf16 v[44:47], v[154:157], v[178:181], v[44:47]
	v_mfma_f32_16x16x32_bf16 v[40:43], v[162:165], v[178:181], v[40:43]
	v_mfma_f32_16x16x32_bf16 v[28:31], v[154:157], v[186:189], v[28:31]
	v_mfma_f32_16x16x32_bf16 v[24:27], v[162:165], v[186:189], v[24:27]
	v_mfma_f32_16x16x32_bf16 v[12:15], v[154:157], v[194:197], v[12:15]
	v_mfma_f32_16x16x32_bf16 v[8:11], v[162:165], v[194:197], v[8:11]
	s_barrier
	s_add_u32 s64, s64, 0x40080
	s_addc_u32 s65, s65, 0
	s_add_i32 s66, s66, s33
	v_lshl_add_u64 v[142:143], s[64:65], 0, v[128:129]
	s_mov_b32 m0, s66
	s_nop 0
	global_load_lds_dwordx4 v[142:143], off
	v_lshl_add_u64 v[142:143], s[64:65], 0, v[130:131]
	s_add_i32 m0, s66, 0x2000
	s_nop 0
	global_load_lds_dwordx4 v[142:143], off
	s_waitcnt vmcnt(6)
	s_barrier
	v_mfma_f32_16x16x32_bf16 v[52:55], v[198:201], v[166:169], v[52:55]
	v_mfma_f32_16x16x32_bf16 v[48:51], v[206:209], v[166:169], v[48:51]
	v_mfma_f32_16x16x32_bf16 v[36:39], v[198:201], v[174:177], v[36:39]
	v_mfma_f32_16x16x32_bf16 v[32:35], v[206:209], v[174:177], v[32:35]
	v_mfma_f32_16x16x32_bf16 v[20:23], v[198:201], v[182:185], v[20:23]
	v_mfma_f32_16x16x32_bf16 v[16:19], v[206:209], v[182:185], v[16:19]
	v_mfma_f32_16x16x32_bf16 v[4:7], v[198:201], v[190:193], v[4:7]
	v_mfma_f32_16x16x32_bf16 v[0:3], v[206:209], v[190:193], v[0:3]
	v_mfma_f32_16x16x32_bf16 v[52:55], v[202:205], v[170:173], v[52:55]
	v_mfma_f32_16x16x32_bf16 v[48:51], v[210:213], v[170:173], v[48:51]
	v_mfma_f32_16x16x32_bf16 v[36:39], v[202:205], v[178:181], v[36:39]
	v_mfma_f32_16x16x32_bf16 v[32:35], v[210:213], v[178:181], v[32:35]
	v_mfma_f32_16x16x32_bf16 v[20:23], v[202:205], v[186:189], v[20:23]
	v_mfma_f32_16x16x32_bf16 v[16:19], v[210:213], v[186:189], v[16:19]
	v_mfma_f32_16x16x32_bf16 v[4:7], v[202:205], v[194:197], v[4:7]
	v_mfma_f32_16x16x32_bf16 v[0:3], v[210:213], v[194:197], v[0:3]
	s_add_i32 s85, s85, 2
	s_add_u32 s62, s62, 0x100
	s_addc_u32 s63, s63, 0
	s_add_u32 s83, s83, 0x100
	s_addc_u32 s84, s84, 0
	s_cmp_gt_u32 s85, 13
	s_barrier
	s_cbranch_scc0 .LBB0_668
	s_and_b64 vcc, exec, s[4:5]
	s_cbranch_vccnz .Lp6_last
	v_lshl_add_u32 v150, s52, 8, v144
	s_lshl_b32 s52, s53, 8
	v_and_b32_e32 v152, 1, v150
	v_and_b32_e32 v150, -2, v150
	v_ashrrev_i32_e32 v151, 31, v150
	s_ashr_i32 s53, s52, 31
	v_lshlrev_b64 v[142:143], 13, v[150:151]
	v_lshl_add_u64 v[142:143], s[30:31], 0, v[142:143]
	s_lshl_b64 s[52:53], s[52:53], 1
	v_lshl_add_u64 v[142:143], v[142:143], 0, s[52:53]
	v_lshl_add_u64 v[142:143], v[142:143], 0, s[6:7]
	v_lshl_add_u64 v[142:143], v[142:143], 0, s[6:7]
	v_lshl_add_u32 v152, v152, 6, v132
	v_mov_b32_e32 v153, 0
	v_lshl_add_u64 v[142:143], v[142:143], 0, v[152:153]
	s_mov_b64 s[90:91], 0x20000
	s_mov_b64 s[66:67], 0x2000
	s_mov_b32 s86, 0x55555555
	s_mov_b32 s87, 0x55555555
	s_mov_b32 s88, 0xaaaaaaaa
	s_mov_b32 s89, 0xaaaaaaaa
	v_max_f32_e32 v124, 0, v124
	v_max_f32_e32 v125, 0, v125
	v_max_f32_e32 v126, 0, v126
	v_max_f32_e32 v127, 0, v127
	v_max_f32_e32 v120, 0, v120
	v_max_f32_e32 v121, 0, v121
	v_max_f32_e32 v122, 0, v122
	v_max_f32_e32 v123, 0, v123
	v_pk_mul_f32 v[124:125], v[124:125], v[124:125]
	v_pk_mul_f32 v[126:127], v[126:127], v[126:127]
	v_pk_mul_f32 v[120:121], v[120:121], v[120:121]
	v_pk_mul_f32 v[122:123], v[122:123], v[122:123]
	v_cvt_pk_bf16_f32 v124, v124, v125
	v_cvt_pk_bf16_f32 v125, v126, v127
	v_cvt_pk_bf16_f32 v126, v120, v121
	v_cvt_pk_bf16_f32 v127, v122, v123
	v_max_f32_e32 v116, 0, v116
	v_max_f32_e32 v117, 0, v117
	v_max_f32_e32 v118, 0, v118
	v_max_f32_e32 v119, 0, v119
	v_max_f32_e32 v112, 0, v112
	v_max_f32_e32 v113, 0, v113
	v_max_f32_e32 v114, 0, v114
	v_max_f32_e32 v115, 0, v115
	v_pk_mul_f32 v[116:117], v[116:117], v[116:117]
	v_pk_mul_f32 v[118:119], v[118:119], v[118:119]
	v_pk_mul_f32 v[112:113], v[112:113], v[112:113]
	v_pk_mul_f32 v[114:115], v[114:115], v[114:115]
	v_cvt_pk_bf16_f32 v116, v116, v117
	v_cvt_pk_bf16_f32 v117, v118, v119
	v_cvt_pk_bf16_f32 v118, v112, v113
	v_cvt_pk_bf16_f32 v119, v114, v115
	v_lshl_add_u64 v[158:159], v[142:143], 0, s[66:67]
	s_mov_b64 vcc, s[86:87]
	s_nop 0
	v_cndmask_b32_dpp v154, v116, v124, vcc quad_perm:[1,0,3,2] row_mask:0xf bank_mask:0xf
	v_cndmask_b32_dpp v155, v117, v125, vcc quad_perm:[1,0,3,2] row_mask:0xf bank_mask:0xf
	v_cndmask_b32_dpp v156, v118, v126, vcc quad_perm:[1,0,3,2] row_mask:0xf bank_mask:0xf
	v_cndmask_b32_dpp v157, v119, v127, vcc quad_perm:[1,0,3,2] row_mask:0xf bank_mask:0xf
	s_mov_b64 vcc, s[88:89]
	v_cndmask_b32_dpp v116, v124, v116, vcc quad_perm:[1,0,3,2] row_mask:0xf bank_mask:0xf
	v_cndmask_b32_dpp v117, v125, v117, vcc quad_perm:[1,0,3,2] row_mask:0xf bank_mask:0xf
	v_cndmask_b32_dpp v118, v126, v118, vcc quad_perm:[1,0,3,2] row_mask:0xf bank_mask:0xf
	v_cndmask_b32_dpp v119, v127, v119, vcc quad_perm:[1,0,3,2] row_mask:0xf bank_mask:0xf
	global_store_dwordx4 v[142:143], v[154:157], off
	global_store_dwordx4 v[158:159], v[116:119], off
; __device__ __forceinline__ void st_bf16x8(bf16_t* p, const f32x4 a, const f32x4 b) { uint4 o; o.x = cvt_pk_bf16(a[0], a[1]); o.y = cvt_pk_bf16(a[2], a[3]); o.z = cvt_pk_bf16(b[0], b[1]); o.w = cvt_pk_bf16(b[2], b[3]); *(uint4*)p = o; }
;     __device__ __forceinline__ void row(const f32x4 (&a)[2][2], int row, int pn, int wc, int fq) const {
;         bf16_t* rp = T + (size_t)row * DFF + pn * BM + wc * 32 + 8 * fq;
; #pragma unroll
;         for (int bj = 0; bj < 2; ++bj) { f32x4 v0 = a[bj][0], v1 = a[bj][1];
; #pragma unroll
;             for (int j = 0; j < 4; ++j) { const float r0 = fmaxf(v0[j], 0.f), r1 = fmaxf(v1[j], 0.f); v0[j] = r0 * r0; v1[j] = r1 * r1; }
;             st_bf16x8(rp + bj * HALF, v0, v1); }
	v_lshl_add_u64 v[142:143], v[142:143], 0, s[90:91]
	v_max_f32_e32 v108, 0, v108
	v_max_f32_e32 v109, 0, v109
	v_max_f32_e32 v110, 0, v110
	v_max_f32_e32 v111, 0, v111
	v_max_f32_e32 v104, 0, v104
	v_max_f32_e32 v105, 0, v105
	v_max_f32_e32 v106, 0, v106
	v_max_f32_e32 v107, 0, v107
	v_pk_mul_f32 v[108:109], v[108:109], v[108:109]
	v_pk_mul_f32 v[110:111], v[110:111], v[110:111]
	v_pk_mul_f32 v[104:105], v[104:105], v[104:105]
	v_pk_mul_f32 v[106:107], v[106:107], v[106:107]
	v_cvt_pk_bf16_f32 v108, v108, v109
	v_cvt_pk_bf16_f32 v109, v110, v111
	v_cvt_pk_bf16_f32 v110, v104, v105
	v_cvt_pk_bf16_f32 v111, v106, v107
	v_max_f32_e32 v100, 0, v100
	v_max_f32_e32 v101, 0, v101
	v_max_f32_e32 v102, 0, v102
	v_max_f32_e32 v103, 0, v103
	v_max_f32_e32 v96, 0, v96
	v_max_f32_e32 v97, 0, v97
	v_max_f32_e32 v98, 0, v98
	v_max_f32_e32 v99, 0, v99
	v_pk_mul_f32 v[100:101], v[100:101], v[100:101]
	v_pk_mul_f32 v[102:103], v[102:103], v[102:103]
	v_pk_mul_f32 v[96:97], v[96:97], v[96:97]
	v_pk_mul_f32 v[98:99], v[98:99], v[98:99]
	v_cvt_pk_bf16_f32 v100, v100, v101
	v_cvt_pk_bf16_f32 v101, v102, v103
	v_cvt_pk_bf16_f32 v102, v96, v97
	v_cvt_pk_bf16_f32 v103, v98, v99
	v_lshl_add_u64 v[158:159], v[142:143], 0, s[66:67]
	s_mov_b64 vcc, s[86:87]
	s_nop 0
	v_cndmask_b32_dpp v154, v100, v108, vcc quad_perm:[1,0,3,2] row_mask:0xf bank_mask:0xf
	v_cndmask_b32_dpp v155, v101, v109, vcc quad_perm:[1,0,3,2] row_mask:0xf bank_mask:0xf
	v_cndmask_b32_dpp v156, v102, v110, vcc quad_perm:[1,0,3,2] row_mask:0xf bank_mask:0xf
	v_cndmask_b32_dpp v157, v103, v111, vcc quad_perm:[1,0,3,2] row_mask:0xf bank_mask:0xf
	s_mov_b64 vcc, s[88:89]
	v_cndmask_b32_dpp v100, v108, v100, vcc quad_perm:[1,0,3,2] row_mask:0xf bank_mask:0xf
	v_cndmask_b32_dpp v101, v109, v101, vcc quad_perm:[1,0,3,2] row_mask:0xf bank_mask:0xf
	v_cndmask_b32_dpp v102, v110, v102, vcc quad_perm:[1,0,3,2] row_mask:0xf bank_mask:0xf
	v_cndmask_b32_dpp v103, v111, v103, vcc quad_perm:[1,0,3,2] row_mask:0xf bank_mask:0xf
	global_store_dwordx4 v[142:143], v[154:157], off
	global_store_dwordx4 v[158:159], v[100:103], off
	v_lshl_add_u64 v[142:143], v[142:143], 0, s[90:91]
	v_max_f32_e32 v92, 0, v92
	v_max_f32_e32 v93, 0, v93
	v_max_f32_e32 v94, 0, v94
	v_max_f32_e32 v95, 0, v95
	v_max_f32_e32 v88, 0, v88
	v_max_f32_e32 v89, 0, v89
	v_max_f32_e32 v90, 0, v90
	v_max_f32_e32 v91, 0, v91
	v_pk_mul_f32 v[92:93], v[92:93], v[92:93]
	v_pk_mul_f32 v[94:95], v[94:95], v[94:95]
	v_pk_mul_f32 v[88:89], v[88:89], v[88:89]
	v_pk_mul_f32 v[90:91], v[90:91], v[90:91]
	v_cvt_pk_bf16_f32 v92, v92, v93
	v_cvt_pk_bf16_f32 v93, v94, v95
	v_cvt_pk_bf16_f32 v94, v88, v89
	v_cvt_pk_bf16_f32 v95, v90, v91
	v_max_f32_e32 v84, 0, v84
	v_max_f32_e32 v85, 0, v85
	v_max_f32_e32 v86, 0, v86
	v_max_f32_e32 v87, 0, v87
	v_max_f32_e32 v80, 0, v80
	v_max_f32_e32 v81, 0, v81
	v_max_f32_e32 v82, 0, v82
	v_max_f32_e32 v83, 0, v83
	v_pk_mul_f32 v[84:85], v[84:85], v[84:85]
	v_pk_mul_f32 v[86:87], v[86:87], v[86:87]
	v_pk_mul_f32 v[80:81], v[80:81], v[80:81]
	v_pk_mul_f32 v[82:83], v[82:83], v[82:83]
	v_cvt_pk_bf16_f32 v84, v84, v85
	v_cvt_pk_bf16_f32 v85, v86, v87
	v_cvt_pk_bf16_f32 v86, v80, v81
	v_cvt_pk_bf16_f32 v87, v82, v83
	v_lshl_add_u64 v[158:159], v[142:143], 0, s[66:67]
	s_mov_b64 vcc, s[86:87]
	s_nop 0
	v_cndmask_b32_dpp v154, v84, v92, vcc quad_perm:[1,0,3,2] row_mask:0xf bank_mask:0xf
	v_cndmask_b32_dpp v155, v85, v93, vcc quad_perm:[1,0,3,2] row_mask:0xf bank_mask:0xf
	v_cndmask_b32_dpp v156, v86, v94, vcc quad_perm:[1,0,3,2] row_mask:0xf bank_mask:0xf
	v_cndmask_b32_dpp v157, v87, v95, vcc quad_perm:[1,0,3,2] row_mask:0xf bank_mask:0xf
	s_mov_b64 vcc, s[88:89]
	v_cndmask_b32_dpp v84, v92, v84, vcc quad_perm:[1,0,3,2] row_mask:0xf bank_mask:0xf
	v_cndmask_b32_dpp v85, v93, v85, vcc quad_perm:[1,0,3,2] row_mask:0xf bank_mask:0xf
	v_cndmask_b32_dpp v86, v94, v86, vcc quad_perm:[1,0,3,2] row_mask:0xf bank_mask:0xf
	v_cndmask_b32_dpp v87, v95, v87, vcc quad_perm:[1,0,3,2] row_mask:0xf bank_mask:0xf
	global_store_dwordx4 v[142:143], v[154:157], off
	global_store_dwordx4 v[158:159], v[84:87], off
	v_lshl_add_u64 v[142:143], v[142:143], 0, s[90:91]
	v_max_f32_e32 v76, 0, v76
	v_max_f32_e32 v77, 0, v77
	v_max_f32_e32 v78, 0, v78
	v_max_f32_e32 v79, 0, v79
	v_max_f32_e32 v72, 0, v72
	v_max_f32_e32 v73, 0, v73
	v_max_f32_e32 v74, 0, v74
	v_max_f32_e32 v75, 0, v75
	v_pk_mul_f32 v[76:77], v[76:77], v[76:77]
	v_pk_mul_f32 v[78:79], v[78:79], v[78:79]
	v_pk_mul_f32 v[72:73], v[72:73], v[72:73]
	v_pk_mul_f32 v[74:75], v[74:75], v[74:75]
	v_cvt_pk_bf16_f32 v76, v76, v77
	v_cvt_pk_bf16_f32 v77, v78, v79
	v_cvt_pk_bf16_f32 v78, v72, v73
	v_cvt_pk_bf16_f32 v79, v74, v75
	v_max_f32_e32 v68, 0, v68
	v_max_f32_e32 v69, 0, v69
	v_max_f32_e32 v70, 0, v70
	v_max_f32_e32 v71, 0, v71
	v_max_f32_e32 v64, 0, v64
	v_max_f32_e32 v65, 0, v65
	v_max_f32_e32 v66, 0, v66
	v_max_f32_e32 v67, 0, v67
	v_pk_mul_f32 v[68:69], v[68:69], v[68:69]
	v_pk_mul_f32 v[70:71], v[70:71], v[70:71]
	v_pk_mul_f32 v[64:65], v[64:65], v[64:65]
	v_pk_mul_f32 v[66:67], v[66:67], v[66:67]
	v_cvt_pk_bf16_f32 v68, v68, v69
	v_cvt_pk_bf16_f32 v69, v70, v71
	v_cvt_pk_bf16_f32 v70, v64, v65
	v_cvt_pk_bf16_f32 v71, v66, v67
	v_lshl_add_u64 v[158:159], v[142:143], 0, s[66:67]
	s_mov_b64 vcc, s[86:87]
	s_nop 0
	v_cndmask_b32_dpp v154, v68, v76, vcc quad_perm:[1,0,3,2] row_mask:0xf bank_mask:0xf
	v_cndmask_b32_dpp v155, v69, v77, vcc quad_perm:[1,0,3,2] row_mask:0xf bank_mask:0xf
	v_cndmask_b32_dpp v156, v70, v78, vcc quad_perm:[1,0,3,2] row_mask:0xf bank_mask:0xf
	v_cndmask_b32_dpp v157, v71, v79, vcc quad_perm:[1,0,3,2] row_mask:0xf bank_mask:0xf
	s_mov_b64 vcc, s[88:89]
; __device__ __forceinline__ void st_bf16x8(bf16_t* p, const f32x4 a, const f32x4 b) { uint4 o; o.x = cvt_pk_bf16(a[0], a[1]); o.y = cvt_pk_bf16(a[2], a[3]); o.z = cvt_pk_bf16(b[0], b[1]); o.w = cvt_pk_bf16(b[2], b[3]); *(uint4*)p = o; }
;     __device__ __forceinline__ void row(const f32x4 (&a)[2][2], int row, int pn, int wc, int fq) const {
;         bf16_t* rp = T + (size_t)row * DFF + pn * BM + wc * 32 + 8 * fq;
; #pragma unroll
;         for (int bj = 0; bj < 2; ++bj) { f32x4 v0 = a[bj][0], v1 = a[bj][1];
; #pragma unroll
;             for (int j = 0; j < 4; ++j) { const float r0 = fmaxf(v0[j], 0.f), r1 = fmaxf(v1[j], 0.f); v0[j] = r0 * r0; v1[j] = r1 * r1; }
;             st_bf16x8(rp + bj * HALF, v0, v1); }
	v_cndmask_b32_dpp v68, v76, v68, vcc quad_perm:[1,0,3,2] row_mask:0xf bank_mask:0xf
	v_cndmask_b32_dpp v69, v77, v69, vcc quad_perm:[1,0,3,2] row_mask:0xf bank_mask:0xf
	v_cndmask_b32_dpp v70, v78, v70, vcc quad_perm:[1,0,3,2] row_mask:0xf bank_mask:0xf
	v_cndmask_b32_dpp v71, v79, v71, vcc quad_perm:[1,0,3,2] row_mask:0xf bank_mask:0xf
	global_store_dwordx4 v[142:143], v[154:157], off
	global_store_dwordx4 v[158:159], v[68:71], off
	s_mov_b64 s[90:91], 0xa0000
	v_lshl_add_u64 v[142:143], v[142:143], 0, s[90:91]
	s_mov_b64 s[90:91], 0x20000
	v_max_f32_e32 v60, 0, v60
	v_max_f32_e32 v61, 0, v61
	v_max_f32_e32 v62, 0, v62
	v_max_f32_e32 v63, 0, v63
	v_max_f32_e32 v56, 0, v56
	v_max_f32_e32 v57, 0, v57
	v_max_f32_e32 v58, 0, v58
	v_max_f32_e32 v59, 0, v59
	v_pk_mul_f32 v[60:61], v[60:61], v[60:61]
	v_pk_mul_f32 v[62:63], v[62:63], v[62:63]
	v_pk_mul_f32 v[56:57], v[56:57], v[56:57]
	v_pk_mul_f32 v[58:59], v[58:59], v[58:59]
	v_cvt_pk_bf16_f32 v60, v60, v61
	v_cvt_pk_bf16_f32 v61, v62, v63
	v_cvt_pk_bf16_f32 v62, v56, v57
	v_cvt_pk_bf16_f32 v63, v58, v59
	v_max_f32_e32 v52, 0, v52
	v_max_f32_e32 v53, 0, v53
	v_max_f32_e32 v54, 0, v54
	v_max_f32_e32 v55, 0, v55
	v_max_f32_e32 v48, 0, v48
	v_max_f32_e32 v49, 0, v49
	v_max_f32_e32 v50, 0, v50
	v_max_f32_e32 v51, 0, v51
	v_pk_mul_f32 v[52:53], v[52:53], v[52:53]
	v_pk_mul_f32 v[54:55], v[54:55], v[54:55]
	v_pk_mul_f32 v[48:49], v[48:49], v[48:49]
	v_pk_mul_f32 v[50:51], v[50:51], v[50:51]
	v_cvt_pk_bf16_f32 v52, v52, v53
	v_cvt_pk_bf16_f32 v53, v54, v55
	v_cvt_pk_bf16_f32 v54, v48, v49
	v_cvt_pk_bf16_f32 v55, v50, v51
	v_lshl_add_u64 v[158:159], v[142:143], 0, s[66:67]
	s_mov_b64 vcc, s[86:87]
	s_nop 0
	v_cndmask_b32_dpp v154, v52, v60, vcc quad_perm:[1,0,3,2] row_mask:0xf bank_mask:0xf
	v_cndmask_b32_dpp v155, v53, v61, vcc quad_perm:[1,0,3,2] row_mask:0xf bank_mask:0xf
	v_cndmask_b32_dpp v156, v54, v62, vcc quad_perm:[1,0,3,2] row_mask:0xf bank_mask:0xf
	v_cndmask_b32_dpp v157, v55, v63, vcc quad_perm:[1,0,3,2] row_mask:0xf bank_mask:0xf
	s_mov_b64 vcc, s[88:89]
	v_cndmask_b32_dpp v52, v60, v52, vcc quad_perm:[1,0,3,2] row_mask:0xf bank_mask:0xf
	v_cndmask_b32_dpp v53, v61, v53, vcc quad_perm:[1,0,3,2] row_mask:0xf bank_mask:0xf
	v_cndmask_b32_dpp v54, v62, v54, vcc quad_perm:[1,0,3,2] row_mask:0xf bank_mask:0xf
	v_cndmask_b32_dpp v55, v63, v55, vcc quad_perm:[1,0,3,2] row_mask:0xf bank_mask:0xf
	global_store_dwordx4 v[142:143], v[154:157], off
	global_store_dwordx4 v[158:159], v[52:55], off
	v_lshl_add_u64 v[142:143], v[142:143], 0, s[90:91]
	v_max_f32_e32 v44, 0, v44
	v_max_f32_e32 v45, 0, v45
	v_max_f32_e32 v46, 0, v46
	v_max_f32_e32 v47, 0, v47
	v_max_f32_e32 v40, 0, v40
	v_max_f32_e32 v41, 0, v41
	v_max_f32_e32 v42, 0, v42
	v_max_f32_e32 v43, 0, v43
	v_pk_mul_f32 v[44:45], v[44:45], v[44:45]
	v_pk_mul_f32 v[46:47], v[46:47], v[46:47]
	v_pk_mul_f32 v[40:41], v[40:41], v[40:41]
	v_pk_mul_f32 v[42:43], v[42:43], v[42:43]
	v_cvt_pk_bf16_f32 v44, v44, v45
	v_cvt_pk_bf16_f32 v45, v46, v47
	v_cvt_pk_bf16_f32 v46, v40, v41
	v_cvt_pk_bf16_f32 v47, v42, v43
	v_max_f32_e32 v36, 0, v36
	v_max_f32_e32 v37, 0, v37
	v_max_f32_e32 v38, 0, v38
	v_max_f32_e32 v39, 0, v39
	v_max_f32_e32 v32, 0, v32
	v_max_f32_e32 v33, 0, v33
	v_max_f32_e32 v34, 0, v34
	v_max_f32_e32 v35, 0, v35
	v_pk_mul_f32 v[36:37], v[36:37], v[36:37]
	v_pk_mul_f32 v[38:39], v[38:39], v[38:39]
	v_pk_mul_f32 v[32:33], v[32:33], v[32:33]
	v_pk_mul_f32 v[34:35], v[34:35], v[34:35]
	v_cvt_pk_bf16_f32 v36, v36, v37
	v_cvt_pk_bf16_f32 v37, v38, v39
	v_cvt_pk_bf16_f32 v38, v32, v33
	v_cvt_pk_bf16_f32 v39, v34, v35
	v_lshl_add_u64 v[158:159], v[142:143], 0, s[66:67]
	s_mov_b64 vcc, s[86:87]
	s_nop 0
	v_cndmask_b32_dpp v154, v36, v44, vcc quad_perm:[1,0,3,2] row_mask:0xf bank_mask:0xf
	v_cndmask_b32_dpp v155, v37, v45, vcc quad_perm:[1,0,3,2] row_mask:0xf bank_mask:0xf
	v_cndmask_b32_dpp v156, v38, v46, vcc quad_perm:[1,0,3,2] row_mask:0xf bank_mask:0xf
	v_cndmask_b32_dpp v157, v39, v47, vcc quad_perm:[1,0,3,2] row_mask:0xf bank_mask:0xf
	s_mov_b64 vcc, s[88:89]
	v_cndmask_b32_dpp v36, v44, v36, vcc quad_perm:[1,0,3,2] row_mask:0xf bank_mask:0xf
	v_cndmask_b32_dpp v37, v45, v37, vcc quad_perm:[1,0,3,2] row_mask:0xf bank_mask:0xf
	v_cndmask_b32_dpp v38, v46, v38, vcc quad_perm:[1,0,3,2] row_mask:0xf bank_mask:0xf
	v_cndmask_b32_dpp v39, v47, v39, vcc quad_perm:[1,0,3,2] row_mask:0xf bank_mask:0xf
	global_store_dwordx4 v[142:143], v[154:157], off
	global_store_dwordx4 v[158:159], v[36:39], off
	v_lshl_add_u64 v[142:143], v[142:143], 0, s[90:91]
	v_max_f32_e32 v28, 0, v28
	v_max_f32_e32 v29, 0, v29
	v_max_f32_e32 v30, 0, v30
	v_max_f32_e32 v31, 0, v31
	v_max_f32_e32 v24, 0, v24
	v_max_f32_e32 v25, 0, v25
	v_max_f32_e32 v26, 0, v26
	v_max_f32_e32 v27, 0, v27
	v_pk_mul_f32 v[28:29], v[28:29], v[28:29]
	v_pk_mul_f32 v[30:31], v[30:31], v[30:31]
	v_pk_mul_f32 v[24:25], v[24:25], v[24:25]
	v_pk_mul_f32 v[26:27], v[26:27], v[26:27]
	v_cvt_pk_bf16_f32 v28, v28, v29
	v_cvt_pk_bf16_f32 v29, v30, v31
	v_cvt_pk_bf16_f32 v30, v24, v25
	v_cvt_pk_bf16_f32 v31, v26, v27
	v_max_f32_e32 v20, 0, v20
	v_max_f32_e32 v21, 0, v21
	v_max_f32_e32 v22, 0, v22
	v_max_f32_e32 v23, 0, v23
	v_max_f32_e32 v16, 0, v16
	v_max_f32_e32 v17, 0, v17
	v_max_f32_e32 v18, 0, v18
	v_max_f32_e32 v19, 0, v19
	v_pk_mul_f32 v[20:21], v[20:21], v[20:21]
	v_pk_mul_f32 v[22:23], v[22:23], v[22:23]
	v_pk_mul_f32 v[16:17], v[16:17], v[16:17]
	v_pk_mul_f32 v[18:19], v[18:19], v[18:19]
	v_cvt_pk_bf16_f32 v20, v20, v21
	v_cvt_pk_bf16_f32 v21, v22, v23
	v_cvt_pk_bf16_f32 v22, v16, v17
	v_cvt_pk_bf16_f32 v23, v18, v19
	v_lshl_add_u64 v[158:159], v[142:143], 0, s[66:67]
	s_mov_b64 vcc, s[86:87]
	s_nop 0
; __device__ __forceinline__ void st_bf16x8(bf16_t* p, const f32x4 a, const f32x4 b) { uint4 o; o.x = cvt_pk_bf16(a[0], a[1]); o.y = cvt_pk_bf16(a[2], a[3]); o.z = cvt_pk_bf16(b[0], b[1]); o.w = cvt_pk_bf16(b[2], b[3]); *(uint4*)p = o; }
;     __device__ __forceinline__ void row(const f32x4 (&a)[2][2], int row, int pn, int wc, int fq) const {
;         bf16_t* rp = T + (size_t)row * DFF + pn * BM + wc * 32 + 8 * fq;
; #pragma unroll
;         for (int bj = 0; bj < 2; ++bj) { f32x4 v0 = a[bj][0], v1 = a[bj][1];
; #pragma unroll
;             for (int j = 0; j < 4; ++j) { const float r0 = fmaxf(v0[j], 0.f), r1 = fmaxf(v1[j], 0.f); v0[j] = r0 * r0; v1[j] = r1 * r1; }
;             st_bf16x8(rp + bj * HALF, v0, v1); }
	v_cndmask_b32_dpp v154, v20, v28, vcc quad_perm:[1,0,3,2] row_mask:0xf bank_mask:0xf
	v_cndmask_b32_dpp v155, v21, v29, vcc quad_perm:[1,0,3,2] row_mask:0xf bank_mask:0xf
	v_cndmask_b32_dpp v156, v22, v30, vcc quad_perm:[1,0,3,2] row_mask:0xf bank_mask:0xf
	v_cndmask_b32_dpp v157, v23, v31, vcc quad_perm:[1,0,3,2] row_mask:0xf bank_mask:0xf
	s_mov_b64 vcc, s[88:89]
	v_cndmask_b32_dpp v20, v28, v20, vcc quad_perm:[1,0,3,2] row_mask:0xf bank_mask:0xf
	v_cndmask_b32_dpp v21, v29, v21, vcc quad_perm:[1,0,3,2] row_mask:0xf bank_mask:0xf
	v_cndmask_b32_dpp v22, v30, v22, vcc quad_perm:[1,0,3,2] row_mask:0xf bank_mask:0xf
	v_cndmask_b32_dpp v23, v31, v23, vcc quad_perm:[1,0,3,2] row_mask:0xf bank_mask:0xf
	global_store_dwordx4 v[142:143], v[154:157], off
	global_store_dwordx4 v[158:159], v[20:23], off
	v_lshl_add_u64 v[142:143], v[142:143], 0, s[90:91]
	v_max_f32_e32 v12, 0, v12
	v_max_f32_e32 v13, 0, v13
	v_max_f32_e32 v14, 0, v14
	v_max_f32_e32 v15, 0, v15
	v_max_f32_e32 v8, 0, v8
	v_max_f32_e32 v9, 0, v9
	v_max_f32_e32 v10, 0, v10
	v_max_f32_e32 v11, 0, v11
	v_pk_mul_f32 v[12:13], v[12:13], v[12:13]
	v_pk_mul_f32 v[14:15], v[14:15], v[14:15]
	v_pk_mul_f32 v[8:9], v[8:9], v[8:9]
	v_pk_mul_f32 v[10:11], v[10:11], v[10:11]
	v_cvt_pk_bf16_f32 v12, v12, v13
	v_cvt_pk_bf16_f32 v13, v14, v15
	v_cvt_pk_bf16_f32 v14, v8, v9
	v_cvt_pk_bf16_f32 v15, v10, v11
	v_max_f32_e32 v4, 0, v4
	v_max_f32_e32 v5, 0, v5
	v_max_f32_e32 v6, 0, v6
	v_max_f32_e32 v7, 0, v7
	v_max_f32_e32 v0, 0, v0
	v_max_f32_e32 v1, 0, v1
	v_max_f32_e32 v2, 0, v2
	v_max_f32_e32 v3, 0, v3
	v_pk_mul_f32 v[4:5], v[4:5], v[4:5]
	v_pk_mul_f32 v[6:7], v[6:7], v[6:7]
	v_pk_mul_f32 v[0:1], v[0:1], v[0:1]
	v_pk_mul_f32 v[2:3], v[2:3], v[2:3]
	v_cvt_pk_bf16_f32 v4, v4, v5
	v_cvt_pk_bf16_f32 v5, v6, v7
	v_cvt_pk_bf16_f32 v6, v0, v1
	v_cvt_pk_bf16_f32 v7, v2, v3
	v_lshl_add_u64 v[158:159], v[142:143], 0, s[66:67]
	s_mov_b64 vcc, s[86:87]
	s_nop 0
	v_cndmask_b32_dpp v154, v4, v12, vcc quad_perm:[1,0,3,2] row_mask:0xf bank_mask:0xf
	v_cndmask_b32_dpp v155, v5, v13, vcc quad_perm:[1,0,3,2] row_mask:0xf bank_mask:0xf
	v_cndmask_b32_dpp v156, v6, v14, vcc quad_perm:[1,0,3,2] row_mask:0xf bank_mask:0xf
	v_cndmask_b32_dpp v157, v7, v15, vcc quad_perm:[1,0,3,2] row_mask:0xf bank_mask:0xf
	s_mov_b64 vcc, s[88:89]
	v_cndmask_b32_dpp v4, v12, v4, vcc quad_perm:[1,0,3,2] row_mask:0xf bank_mask:0xf
	v_cndmask_b32_dpp v5, v13, v5, vcc quad_perm:[1,0,3,2] row_mask:0xf bank_mask:0xf
	v_cndmask_b32_dpp v6, v14, v6, vcc quad_perm:[1,0,3,2] row_mask:0xf bank_mask:0xf
	v_cndmask_b32_dpp v7, v15, v7, vcc quad_perm:[1,0,3,2] row_mask:0xf bank_mask:0xf
	global_store_dwordx4 v[142:143], v[154:157], off
	global_store_dwordx4 v[158:159], v[4:7], off
	s_and_b64 vcc, exec, s[4:5]
	s_mov_b32 s53, s44
	s_mov_b32 s52, s46
	s_mov_b64 s[64:65], s[50:51]
	s_mov_b64 s[62:63], s[48:49]
	s_cbranch_vccz .LBB0_661
	s_branch .Lp6_exit
.Lp6_last:
	v_lshl_add_u32 v150, s52, 8, v144
	s_lshl_b32 s52, s53, 8
	v_and_b32_e32 v152, 1, v150
	v_and_b32_e32 v150, -2, v150
	v_ashrrev_i32_e32 v151, 31, v150
	s_ashr_i32 s53, s52, 31
	v_lshlrev_b64 v[142:143], 13, v[150:151]
	v_lshl_add_u64 v[142:143], s[30:31], 0, v[142:143]
	s_lshl_b64 s[52:53], s[52:53], 1
	v_lshl_add_u64 v[142:143], v[142:143], 0, s[52:53]
	v_lshl_add_u64 v[142:143], v[142:143], 0, s[6:7]
	v_lshl_add_u64 v[142:143], v[142:143], 0, s[6:7]
	v_lshl_add_u32 v152, v152, 6, v132
	v_mov_b32_e32 v153, 0
	v_lshl_add_u64 v[142:143], v[142:143], 0, v[152:153]
	s_mov_b64 s[90:91], 0x20000
	s_mov_b64 s[66:67], 0x2000
	s_mov_b32 s86, 0x55555555
	s_mov_b32 s87, 0x55555555
	s_mov_b32 s88, 0xaaaaaaaa
	s_mov_b32 s89, 0xaaaaaaaa
	v_max_f32_e32 v124, 0, v124
	v_max_f32_e32 v125, 0, v125
	v_max_f32_e32 v126, 0, v126
	v_max_f32_e32 v127, 0, v127
	v_max_f32_e32 v120, 0, v120
	v_max_f32_e32 v121, 0, v121
	v_max_f32_e32 v122, 0, v122
	v_max_f32_e32 v123, 0, v123
	v_pk_mul_f32 v[124:125], v[124:125], v[124:125]
	v_pk_mul_f32 v[126:127], v[126:127], v[126:127]
	v_pk_mul_f32 v[120:121], v[120:121], v[120:121]
	v_pk_mul_f32 v[122:123], v[122:123], v[122:123]
	v_cvt_pk_bf16_f32 v124, v124, v125
	v_cvt_pk_bf16_f32 v125, v126, v127
	v_cvt_pk_bf16_f32 v126, v120, v121
	v_cvt_pk_bf16_f32 v127, v122, v123
	v_max_f32_e32 v116, 0, v116
	v_max_f32_e32 v117, 0, v117
	v_max_f32_e32 v118, 0, v118
	v_max_f32_e32 v119, 0, v119
	v_max_f32_e32 v112, 0, v112
	v_max_f32_e32 v113, 0, v113
	v_max_f32_e32 v114, 0, v114
	v_max_f32_e32 v115, 0, v115
	v_pk_mul_f32 v[116:117], v[116:117], v[116:117]
	v_pk_mul_f32 v[118:119], v[118:119], v[118:119]
	v_pk_mul_f32 v[112:113], v[112:113], v[112:113]
	v_pk_mul_f32 v[114:115], v[114:115], v[114:115]
	v_cvt_pk_bf16_f32 v116, v116, v117
	v_cvt_pk_bf16_f32 v117, v118, v119
	v_cvt_pk_bf16_f32 v118, v112, v113
	v_cvt_pk_bf16_f32 v119, v114, v115
	v_lshl_add_u64 v[158:159], v[142:143], 0, s[66:67]
	s_mov_b64 vcc, s[86:87]
	s_nop 0
	v_cndmask_b32_dpp v154, v116, v124, vcc quad_perm:[1,0,3,2] row_mask:0xf bank_mask:0xf
	v_cndmask_b32_dpp v155, v117, v125, vcc quad_perm:[1,0,3,2] row_mask:0xf bank_mask:0xf
	v_cndmask_b32_dpp v156, v118, v126, vcc quad_perm:[1,0,3,2] row_mask:0xf bank_mask:0xf
	v_cndmask_b32_dpp v157, v119, v127, vcc quad_perm:[1,0,3,2] row_mask:0xf bank_mask:0xf
	s_mov_b64 vcc, s[88:89]
	v_cndmask_b32_dpp v116, v124, v116, vcc quad_perm:[1,0,3,2] row_mask:0xf bank_mask:0xf
	v_cndmask_b32_dpp v117, v125, v117, vcc quad_perm:[1,0,3,2] row_mask:0xf bank_mask:0xf
	v_cndmask_b32_dpp v118, v126, v118, vcc quad_perm:[1,0,3,2] row_mask:0xf bank_mask:0xf
	v_cndmask_b32_dpp v119, v127, v119, vcc quad_perm:[1,0,3,2] row_mask:0xf bank_mask:0xf
	global_store_dwordx4 v[142:143], v[154:157], off sc1
; __device__ __forceinline__ void st_bf16x8(bf16_t* p, const f32x4 a, const f32x4 b) { uint4 o; o.x = cvt_pk_bf16(a[0], a[1]); o.y = cvt_pk_bf16(a[2], a[3]); o.z = cvt_pk_bf16(b[0], b[1]); o.w = cvt_pk_bf16(b[2], b[3]); *(uint4*)p = o; }
;     __device__ __forceinline__ void row(const f32x4 (&a)[2][2], int row, int pn, int wc, int fq) const {
;         bf16_t* rp = T + (size_t)row * DFF + pn * BM + wc * 32 + 8 * fq;
; #pragma unroll
;         for (int bj = 0; bj < 2; ++bj) { f32x4 v0 = a[bj][0], v1 = a[bj][1];
; #pragma unroll
;             for (int j = 0; j < 4; ++j) { const float r0 = fmaxf(v0[j], 0.f), r1 = fmaxf(v1[j], 0.f); v0[j] = r0 * r0; v1[j] = r1 * r1; }
;             st_bf16x8(rp + bj * HALF, v0, v1); }
	global_store_dwordx4 v[158:159], v[116:119], off sc1
	v_lshl_add_u64 v[142:143], v[142:143], 0, s[90:91]
	v_max_f32_e32 v108, 0, v108
	v_max_f32_e32 v109, 0, v109
	v_max_f32_e32 v110, 0, v110
	v_max_f32_e32 v111, 0, v111
	v_max_f32_e32 v104, 0, v104
	v_max_f32_e32 v105, 0, v105
	v_max_f32_e32 v106, 0, v106
	v_max_f32_e32 v107, 0, v107
	v_pk_mul_f32 v[108:109], v[108:109], v[108:109]
	v_pk_mul_f32 v[110:111], v[110:111], v[110:111]
	v_pk_mul_f32 v[104:105], v[104:105], v[104:105]
	v_pk_mul_f32 v[106:107], v[106:107], v[106:107]
	v_cvt_pk_bf16_f32 v108, v108, v109
	v_cvt_pk_bf16_f32 v109, v110, v111
	v_cvt_pk_bf16_f32 v110, v104, v105
	v_cvt_pk_bf16_f32 v111, v106, v107
	v_max_f32_e32 v100, 0, v100
	v_max_f32_e32 v101, 0, v101
	v_max_f32_e32 v102, 0, v102
	v_max_f32_e32 v103, 0, v103
	v_max_f32_e32 v96, 0, v96
	v_max_f32_e32 v97, 0, v97
	v_max_f32_e32 v98, 0, v98
	v_max_f32_e32 v99, 0, v99
	v_pk_mul_f32 v[100:101], v[100:101], v[100:101]
	v_pk_mul_f32 v[102:103], v[102:103], v[102:103]
	v_pk_mul_f32 v[96:97], v[96:97], v[96:97]
	v_pk_mul_f32 v[98:99], v[98:99], v[98:99]
	v_cvt_pk_bf16_f32 v100, v100, v101
	v_cvt_pk_bf16_f32 v101, v102, v103
	v_cvt_pk_bf16_f32 v102, v96, v97
	v_cvt_pk_bf16_f32 v103, v98, v99
	v_lshl_add_u64 v[158:159], v[142:143], 0, s[66:67]
	s_mov_b64 vcc, s[86:87]
	s_nop 0
	v_cndmask_b32_dpp v154, v100, v108, vcc quad_perm:[1,0,3,2] row_mask:0xf bank_mask:0xf
	v_cndmask_b32_dpp v155, v101, v109, vcc quad_perm:[1,0,3,2] row_mask:0xf bank_mask:0xf
	v_cndmask_b32_dpp v156, v102, v110, vcc quad_perm:[1,0,3,2] row_mask:0xf bank_mask:0xf
	v_cndmask_b32_dpp v157, v103, v111, vcc quad_perm:[1,0,3,2] row_mask:0xf bank_mask:0xf
	s_mov_b64 vcc, s[88:89]
	v_cndmask_b32_dpp v100, v108, v100, vcc quad_perm:[1,0,3,2] row_mask:0xf bank_mask:0xf
	v_cndmask_b32_dpp v101, v109, v101, vcc quad_perm:[1,0,3,2] row_mask:0xf bank_mask:0xf
	v_cndmask_b32_dpp v102, v110, v102, vcc quad_perm:[1,0,3,2] row_mask:0xf bank_mask:0xf
	v_cndmask_b32_dpp v103, v111, v103, vcc quad_perm:[1,0,3,2] row_mask:0xf bank_mask:0xf
	global_store_dwordx4 v[142:143], v[154:157], off sc1
	global_store_dwordx4 v[158:159], v[100:103], off sc1
	v_lshl_add_u64 v[142:143], v[142:143], 0, s[90:91]
	v_max_f32_e32 v92, 0, v92
	v_max_f32_e32 v93, 0, v93
	v_max_f32_e32 v94, 0, v94
	v_max_f32_e32 v95, 0, v95
	v_max_f32_e32 v88, 0, v88
	v_max_f32_e32 v89, 0, v89
	v_max_f32_e32 v90, 0, v90
	v_max_f32_e32 v91, 0, v91
	v_pk_mul_f32 v[92:93], v[92:93], v[92:93]
	v_pk_mul_f32 v[94:95], v[94:95], v[94:95]
	v_pk_mul_f32 v[88:89], v[88:89], v[88:89]
	v_pk_mul_f32 v[90:91], v[90:91], v[90:91]
	v_cvt_pk_bf16_f32 v92, v92, v93
	v_cvt_pk_bf16_f32 v93, v94, v95
	v_cvt_pk_bf16_f32 v94, v88, v89
	v_cvt_pk_bf16_f32 v95, v90, v91
	v_max_f32_e32 v84, 0, v84
	v_max_f32_e32 v85, 0, v85
	v_max_f32_e32 v86, 0, v86
	v_max_f32_e32 v87, 0, v87
	v_max_f32_e32 v80, 0, v80
	v_max_f32_e32 v81, 0, v81
	v_max_f32_e32 v82, 0, v82
	v_max_f32_e32 v83, 0, v83
	v_pk_mul_f32 v[84:85], v[84:85], v[84:85]
	v_pk_mul_f32 v[86:87], v[86:87], v[86:87]
	v_pk_mul_f32 v[80:81], v[80:81], v[80:81]
	v_pk_mul_f32 v[82:83], v[82:83], v[82:83]
	v_cvt_pk_bf16_f32 v84, v84, v85
	v_cvt_pk_bf16_f32 v85, v86, v87
	v_cvt_pk_bf16_f32 v86, v80, v81
	v_cvt_pk_bf16_f32 v87, v82, v83
	v_lshl_add_u64 v[158:159], v[142:143], 0, s[66:67]
	s_mov_b64 vcc, s[86:87]
	s_nop 0
	v_cndmask_b32_dpp v154, v84, v92, vcc quad_perm:[1,0,3,2] row_mask:0xf bank_mask:0xf
	v_cndmask_b32_dpp v155, v85, v93, vcc quad_perm:[1,0,3,2] row_mask:0xf bank_mask:0xf
	v_cndmask_b32_dpp v156, v86, v94, vcc quad_perm:[1,0,3,2] row_mask:0xf bank_mask:0xf
	v_cndmask_b32_dpp v157, v87, v95, vcc quad_perm:[1,0,3,2] row_mask:0xf bank_mask:0xf
	s_mov_b64 vcc, s[88:89]
	v_cndmask_b32_dpp v84, v92, v84, vcc quad_perm:[1,0,3,2] row_mask:0xf bank_mask:0xf
	v_cndmask_b32_dpp v85, v93, v85, vcc quad_perm:[1,0,3,2] row_mask:0xf bank_mask:0xf
	v_cndmask_b32_dpp v86, v94, v86, vcc quad_perm:[1,0,3,2] row_mask:0xf bank_mask:0xf
	v_cndmask_b32_dpp v87, v95, v87, vcc quad_perm:[1,0,3,2] row_mask:0xf bank_mask:0xf
	global_store_dwordx4 v[142:143], v[154:157], off sc1
	global_store_dwordx4 v[158:159], v[84:87], off sc1
	v_lshl_add_u64 v[142:143], v[142:143], 0, s[90:91]
	v_max_f32_e32 v76, 0, v76
	v_max_f32_e32 v77, 0, v77
	v_max_f32_e32 v78, 0, v78
	v_max_f32_e32 v79, 0, v79
	v_max_f32_e32 v72, 0, v72
	v_max_f32_e32 v73, 0, v73
	v_max_f32_e32 v74, 0, v74
	v_max_f32_e32 v75, 0, v75
	v_pk_mul_f32 v[76:77], v[76:77], v[76:77]
	v_pk_mul_f32 v[78:79], v[78:79], v[78:79]
	v_pk_mul_f32 v[72:73], v[72:73], v[72:73]
	v_pk_mul_f32 v[74:75], v[74:75], v[74:75]
	v_cvt_pk_bf16_f32 v76, v76, v77
	v_cvt_pk_bf16_f32 v77, v78, v79
	v_cvt_pk_bf16_f32 v78, v72, v73
	v_cvt_pk_bf16_f32 v79, v74, v75
	v_max_f32_e32 v68, 0, v68
	v_max_f32_e32 v69, 0, v69
	v_max_f32_e32 v70, 0, v70
	v_max_f32_e32 v71, 0, v71
	v_max_f32_e32 v64, 0, v64
	v_max_f32_e32 v65, 0, v65
	v_max_f32_e32 v66, 0, v66
	v_max_f32_e32 v67, 0, v67
	v_pk_mul_f32 v[68:69], v[68:69], v[68:69]
	v_pk_mul_f32 v[70:71], v[70:71], v[70:71]
	v_pk_mul_f32 v[64:65], v[64:65], v[64:65]
	v_pk_mul_f32 v[66:67], v[66:67], v[66:67]
	v_cvt_pk_bf16_f32 v68, v68, v69
	v_cvt_pk_bf16_f32 v69, v70, v71
	v_cvt_pk_bf16_f32 v70, v64, v65
	v_cvt_pk_bf16_f32 v71, v66, v67
	v_lshl_add_u64 v[158:159], v[142:143], 0, s[66:67]
	s_mov_b64 vcc, s[86:87]
	s_nop 0
	v_cndmask_b32_dpp v154, v68, v76, vcc quad_perm:[1,0,3,2] row_mask:0xf bank_mask:0xf
	v_cndmask_b32_dpp v155, v69, v77, vcc quad_perm:[1,0,3,2] row_mask:0xf bank_mask:0xf
	v_cndmask_b32_dpp v156, v70, v78, vcc quad_perm:[1,0,3,2] row_mask:0xf bank_mask:0xf
	v_cndmask_b32_dpp v157, v71, v79, vcc quad_perm:[1,0,3,2] row_mask:0xf bank_mask:0xf
; __device__ __forceinline__ void st_bf16x8(bf16_t* p, const f32x4 a, const f32x4 b) { uint4 o; o.x = cvt_pk_bf16(a[0], a[1]); o.y = cvt_pk_bf16(a[2], a[3]); o.z = cvt_pk_bf16(b[0], b[1]); o.w = cvt_pk_bf16(b[2], b[3]); *(uint4*)p = o; }
;     __device__ __forceinline__ void row(const f32x4 (&a)[2][2], int row, int pn, int wc, int fq) const {
;         bf16_t* rp = T + (size_t)row * DFF + pn * BM + wc * 32 + 8 * fq;
; #pragma unroll
;         for (int bj = 0; bj < 2; ++bj) { f32x4 v0 = a[bj][0], v1 = a[bj][1];
; #pragma unroll
;             for (int j = 0; j < 4; ++j) { const float r0 = fmaxf(v0[j], 0.f), r1 = fmaxf(v1[j], 0.f); v0[j] = r0 * r0; v1[j] = r1 * r1; }
;             st_bf16x8(rp + bj * HALF, v0, v1); }
	s_mov_b64 vcc, s[88:89]
	v_cndmask_b32_dpp v68, v76, v68, vcc quad_perm:[1,0,3,2] row_mask:0xf bank_mask:0xf
	v_cndmask_b32_dpp v69, v77, v69, vcc quad_perm:[1,0,3,2] row_mask:0xf bank_mask:0xf
	v_cndmask_b32_dpp v70, v78, v70, vcc quad_perm:[1,0,3,2] row_mask:0xf bank_mask:0xf
	v_cndmask_b32_dpp v71, v79, v71, vcc quad_perm:[1,0,3,2] row_mask:0xf bank_mask:0xf
	global_store_dwordx4 v[142:143], v[154:157], off sc1
	global_store_dwordx4 v[158:159], v[68:71], off sc1
	s_mov_b64 s[90:91], 0xa0000
	v_lshl_add_u64 v[142:143], v[142:143], 0, s[90:91]
	s_mov_b64 s[90:91], 0x20000
	v_max_f32_e32 v60, 0, v60
	v_max_f32_e32 v61, 0, v61
	v_max_f32_e32 v62, 0, v62
	v_max_f32_e32 v63, 0, v63
	v_max_f32_e32 v56, 0, v56
	v_max_f32_e32 v57, 0, v57
	v_max_f32_e32 v58, 0, v58
	v_max_f32_e32 v59, 0, v59
	v_pk_mul_f32 v[60:61], v[60:61], v[60:61]
	v_pk_mul_f32 v[62:63], v[62:63], v[62:63]
	v_pk_mul_f32 v[56:57], v[56:57], v[56:57]
	v_pk_mul_f32 v[58:59], v[58:59], v[58:59]
	v_cvt_pk_bf16_f32 v60, v60, v61
	v_cvt_pk_bf16_f32 v61, v62, v63
	v_cvt_pk_bf16_f32 v62, v56, v57
	v_cvt_pk_bf16_f32 v63, v58, v59
	v_max_f32_e32 v52, 0, v52
	v_max_f32_e32 v53, 0, v53
	v_max_f32_e32 v54, 0, v54
	v_max_f32_e32 v55, 0, v55
	v_max_f32_e32 v48, 0, v48
	v_max_f32_e32 v49, 0, v49
	v_max_f32_e32 v50, 0, v50
	v_max_f32_e32 v51, 0, v51
	v_pk_mul_f32 v[52:53], v[52:53], v[52:53]
	v_pk_mul_f32 v[54:55], v[54:55], v[54:55]
	v_pk_mul_f32 v[48:49], v[48:49], v[48:49]
	v_pk_mul_f32 v[50:51], v[50:51], v[50:51]
	v_cvt_pk_bf16_f32 v52, v52, v53
	v_cvt_pk_bf16_f32 v53, v54, v55
	v_cvt_pk_bf16_f32 v54, v48, v49
	v_cvt_pk_bf16_f32 v55, v50, v51
	v_lshl_add_u64 v[158:159], v[142:143], 0, s[66:67]
	s_mov_b64 vcc, s[86:87]
	s_nop 0
	v_cndmask_b32_dpp v154, v52, v60, vcc quad_perm:[1,0,3,2] row_mask:0xf bank_mask:0xf
	v_cndmask_b32_dpp v155, v53, v61, vcc quad_perm:[1,0,3,2] row_mask:0xf bank_mask:0xf
	v_cndmask_b32_dpp v156, v54, v62, vcc quad_perm:[1,0,3,2] row_mask:0xf bank_mask:0xf
	v_cndmask_b32_dpp v157, v55, v63, vcc quad_perm:[1,0,3,2] row_mask:0xf bank_mask:0xf
	s_mov_b64 vcc, s[88:89]
	v_cndmask_b32_dpp v52, v60, v52, vcc quad_perm:[1,0,3,2] row_mask:0xf bank_mask:0xf
	v_cndmask_b32_dpp v53, v61, v53, vcc quad_perm:[1,0,3,2] row_mask:0xf bank_mask:0xf
	v_cndmask_b32_dpp v54, v62, v54, vcc quad_perm:[1,0,3,2] row_mask:0xf bank_mask:0xf
	v_cndmask_b32_dpp v55, v63, v55, vcc quad_perm:[1,0,3,2] row_mask:0xf bank_mask:0xf
	global_store_dwordx4 v[142:143], v[154:157], off sc1
	global_store_dwordx4 v[158:159], v[52:55], off sc1
	v_lshl_add_u64 v[142:143], v[142:143], 0, s[90:91]
	v_max_f32_e32 v44, 0, v44
	v_max_f32_e32 v45, 0, v45
	v_max_f32_e32 v46, 0, v46
	v_max_f32_e32 v47, 0, v47
	v_max_f32_e32 v40, 0, v40
	v_max_f32_e32 v41, 0, v41
	v_max_f32_e32 v42, 0, v42
	v_max_f32_e32 v43, 0, v43
	v_pk_mul_f32 v[44:45], v[44:45], v[44:45]
	v_pk_mul_f32 v[46:47], v[46:47], v[46:47]
	v_pk_mul_f32 v[40:41], v[40:41], v[40:41]
	v_pk_mul_f32 v[42:43], v[42:43], v[42:43]
	v_cvt_pk_bf16_f32 v44, v44, v45
	v_cvt_pk_bf16_f32 v45, v46, v47
	v_cvt_pk_bf16_f32 v46, v40, v41
	v_cvt_pk_bf16_f32 v47, v42, v43
	v_max_f32_e32 v36, 0, v36
	v_max_f32_e32 v37, 0, v37
	v_max_f32_e32 v38, 0, v38
	v_max_f32_e32 v39, 0, v39
	v_max_f32_e32 v32, 0, v32
	v_max_f32_e32 v33, 0, v33
	v_max_f32_e32 v34, 0, v34
	v_max_f32_e32 v35, 0, v35
	v_pk_mul_f32 v[36:37], v[36:37], v[36:37]
	v_pk_mul_f32 v[38:39], v[38:39], v[38:39]
	v_pk_mul_f32 v[32:33], v[32:33], v[32:33]
	v_pk_mul_f32 v[34:35], v[34:35], v[34:35]
	v_cvt_pk_bf16_f32 v36, v36, v37
	v_cvt_pk_bf16_f32 v37, v38, v39
	v_cvt_pk_bf16_f32 v38, v32, v33
	v_cvt_pk_bf16_f32 v39, v34, v35
	v_lshl_add_u64 v[158:159], v[142:143], 0, s[66:67]
	s_mov_b64 vcc, s[86:87]
	s_nop 0
	v_cndmask_b32_dpp v154, v36, v44, vcc quad_perm:[1,0,3,2] row_mask:0xf bank_mask:0xf
	v_cndmask_b32_dpp v155, v37, v45, vcc quad_perm:[1,0,3,2] row_mask:0xf bank_mask:0xf
	v_cndmask_b32_dpp v156, v38, v46, vcc quad_perm:[1,0,3,2] row_mask:0xf bank_mask:0xf
	v_cndmask_b32_dpp v157, v39, v47, vcc quad_perm:[1,0,3,2] row_mask:0xf bank_mask:0xf
	s_mov_b64 vcc, s[88:89]
	v_cndmask_b32_dpp v36, v44, v36, vcc quad_perm:[1,0,3,2] row_mask:0xf bank_mask:0xf
	v_cndmask_b32_dpp v37, v45, v37, vcc quad_perm:[1,0,3,2] row_mask:0xf bank_mask:0xf
	v_cndmask_b32_dpp v38, v46, v38, vcc quad_perm:[1,0,3,2] row_mask:0xf bank_mask:0xf
; __device__ __forceinline__ void st_bf16x8(bf16_t* p, const f32x4 a, const f32x4 b) { uint4 o; o.x = cvt_pk_bf16(a[0], a[1]); o.y = cvt_pk_bf16(a[2], a[3]); o.z = cvt_pk_bf16(b[0], b[1]); o.w = cvt_pk_bf16(b[2], b[3]); *(uint4*)p = o; }
; #define PG8_WAIT_V(n) asm volatile("s_waitcnt vmcnt(" #n ")" ::: "memory")
; #define PG8_BAR __builtin_amdgcn_s_barrier()
;     __device__ __forceinline__ void row(const f32x4 (&a)[2][2], int row, int pn, int wc, int fq) const {
;         bf16_t* rp = T + (size_t)row * DFF + pn * BM + wc * 32 + 8 * fq;
; #pragma unroll
;         for (int bj = 0; bj < 2; ++bj) { f32x4 v0 = a[bj][0], v1 = a[bj][1];
; #pragma unroll
;             for (int j = 0; j < 4; ++j) { const float r0 = fmaxf(v0[j], 0.f), r1 = fmaxf(v1[j], 0.f); v0[j] = r0 * r0; v1[j] = r1 * r1; }
;             st_bf16x8(rp + bj * HALF, v0, v1); }
; template <class Epi>
; __device__ __forceinline__ void gemm_phase(LAS unsigned char* lds, const Gemm g, const StaticOrder& S, const Epi& E, float* smem = nullptr) {
;     ...
;     PG8_WAIT_V(0);
;     if (wr == 0) PG8_BAR;
;     PG8_BAR;
	v_cndmask_b32_dpp v39, v47, v39, vcc quad_perm:[1,0,3,2] row_mask:0xf bank_mask:0xf
	global_store_dwordx4 v[142:143], v[154:157], off sc1
	global_store_dwordx4 v[158:159], v[36:39], off sc1
	v_lshl_add_u64 v[142:143], v[142:143], 0, s[90:91]
	v_max_f32_e32 v28, 0, v28
	v_max_f32_e32 v29, 0, v29
	v_max_f32_e32 v30, 0, v30
	v_max_f32_e32 v31, 0, v31
	v_max_f32_e32 v24, 0, v24
	v_max_f32_e32 v25, 0, v25
	v_max_f32_e32 v26, 0, v26
	v_max_f32_e32 v27, 0, v27
	v_pk_mul_f32 v[28:29], v[28:29], v[28:29]
	v_pk_mul_f32 v[30:31], v[30:31], v[30:31]
	v_pk_mul_f32 v[24:25], v[24:25], v[24:25]
	v_pk_mul_f32 v[26:27], v[26:27], v[26:27]
	v_cvt_pk_bf16_f32 v28, v28, v29
	v_cvt_pk_bf16_f32 v29, v30, v31
	v_cvt_pk_bf16_f32 v30, v24, v25
	v_cvt_pk_bf16_f32 v31, v26, v27
	v_max_f32_e32 v20, 0, v20
	v_max_f32_e32 v21, 0, v21
	v_max_f32_e32 v22, 0, v22
	v_max_f32_e32 v23, 0, v23
	v_max_f32_e32 v16, 0, v16
	v_max_f32_e32 v17, 0, v17
	v_max_f32_e32 v18, 0, v18
	v_max_f32_e32 v19, 0, v19
	v_pk_mul_f32 v[20:21], v[20:21], v[20:21]
	v_pk_mul_f32 v[22:23], v[22:23], v[22:23]
	v_pk_mul_f32 v[16:17], v[16:17], v[16:17]
	v_pk_mul_f32 v[18:19], v[18:19], v[18:19]
	v_cvt_pk_bf16_f32 v20, v20, v21
	v_cvt_pk_bf16_f32 v21, v22, v23
	v_cvt_pk_bf16_f32 v22, v16, v17
	v_cvt_pk_bf16_f32 v23, v18, v19
	v_lshl_add_u64 v[158:159], v[142:143], 0, s[66:67]
	s_mov_b64 vcc, s[86:87]
	s_nop 0
	v_cndmask_b32_dpp v154, v20, v28, vcc quad_perm:[1,0,3,2] row_mask:0xf bank_mask:0xf
	v_cndmask_b32_dpp v155, v21, v29, vcc quad_perm:[1,0,3,2] row_mask:0xf bank_mask:0xf
	v_cndmask_b32_dpp v156, v22, v30, vcc quad_perm:[1,0,3,2] row_mask:0xf bank_mask:0xf
	v_cndmask_b32_dpp v157, v23, v31, vcc quad_perm:[1,0,3,2] row_mask:0xf bank_mask:0xf
	s_mov_b64 vcc, s[88:89]
	v_cndmask_b32_dpp v20, v28, v20, vcc quad_perm:[1,0,3,2] row_mask:0xf bank_mask:0xf
	v_cndmask_b32_dpp v21, v29, v21, vcc quad_perm:[1,0,3,2] row_mask:0xf bank_mask:0xf
	v_cndmask_b32_dpp v22, v30, v22, vcc quad_perm:[1,0,3,2] row_mask:0xf bank_mask:0xf
	v_cndmask_b32_dpp v23, v31, v23, vcc quad_perm:[1,0,3,2] row_mask:0xf bank_mask:0xf
	global_store_dwordx4 v[142:143], v[154:157], off sc1
	global_store_dwordx4 v[158:159], v[20:23], off sc1
	v_lshl_add_u64 v[142:143], v[142:143], 0, s[90:91]
	v_max_f32_e32 v12, 0, v12
	v_max_f32_e32 v13, 0, v13
	v_max_f32_e32 v14, 0, v14
	v_max_f32_e32 v15, 0, v15
	v_max_f32_e32 v8, 0, v8
	v_max_f32_e32 v9, 0, v9
	v_max_f32_e32 v10, 0, v10
	v_max_f32_e32 v11, 0, v11
	v_pk_mul_f32 v[12:13], v[12:13], v[12:13]
	v_pk_mul_f32 v[14:15], v[14:15], v[14:15]
	v_pk_mul_f32 v[8:9], v[8:9], v[8:9]
	v_pk_mul_f32 v[10:11], v[10:11], v[10:11]
	v_cvt_pk_bf16_f32 v12, v12, v13
	v_cvt_pk_bf16_f32 v13, v14, v15
	v_cvt_pk_bf16_f32 v14, v8, v9
	v_cvt_pk_bf16_f32 v15, v10, v11
	v_max_f32_e32 v4, 0, v4
	v_max_f32_e32 v5, 0, v5
	v_max_f32_e32 v6, 0, v6
	v_max_f32_e32 v7, 0, v7
	v_max_f32_e32 v0, 0, v0
	v_max_f32_e32 v1, 0, v1
	v_max_f32_e32 v2, 0, v2
	v_max_f32_e32 v3, 0, v3
	v_pk_mul_f32 v[4:5], v[4:5], v[4:5]
	v_pk_mul_f32 v[6:7], v[6:7], v[6:7]
	v_pk_mul_f32 v[0:1], v[0:1], v[0:1]
	v_pk_mul_f32 v[2:3], v[2:3], v[2:3]
	v_cvt_pk_bf16_f32 v4, v4, v5
	v_cvt_pk_bf16_f32 v5, v6, v7
	v_cvt_pk_bf16_f32 v6, v0, v1
	v_cvt_pk_bf16_f32 v7, v2, v3
	v_lshl_add_u64 v[158:159], v[142:143], 0, s[66:67]
	s_mov_b64 vcc, s[86:87]
	s_nop 0
	v_cndmask_b32_dpp v154, v4, v12, vcc quad_perm:[1,0,3,2] row_mask:0xf bank_mask:0xf
	v_cndmask_b32_dpp v155, v5, v13, vcc quad_perm:[1,0,3,2] row_mask:0xf bank_mask:0xf
	v_cndmask_b32_dpp v156, v6, v14, vcc quad_perm:[1,0,3,2] row_mask:0xf bank_mask:0xf
	v_cndmask_b32_dpp v157, v7, v15, vcc quad_perm:[1,0,3,2] row_mask:0xf bank_mask:0xf
	s_mov_b64 vcc, s[88:89]
	v_cndmask_b32_dpp v4, v12, v4, vcc quad_perm:[1,0,3,2] row_mask:0xf bank_mask:0xf
	v_cndmask_b32_dpp v5, v13, v5, vcc quad_perm:[1,0,3,2] row_mask:0xf bank_mask:0xf
	v_cndmask_b32_dpp v6, v14, v6, vcc quad_perm:[1,0,3,2] row_mask:0xf bank_mask:0xf
	v_cndmask_b32_dpp v7, v15, v7, vcc quad_perm:[1,0,3,2] row_mask:0xf bank_mask:0xf
	global_store_dwordx4 v[142:143], v[154:157], off sc1
	global_store_dwordx4 v[158:159], v[4:7], off sc1
	s_and_b64 vcc, exec, s[4:5]
	s_mov_b32 s53, s44
	s_mov_b32 s52, s46
	s_mov_b64 s[64:65], s[50:51]
	s_mov_b64 s[62:63], s[48:49]
.Lp6_exit:
	s_waitcnt vmcnt(0)
	s_cmpk_gt_u32 s12, 0xff
	s_cbranch_scc1 .LBB0_672
	s_barrier
.LBB0_672:
	s_barrier
